# k_rope (tile 25) epilogue loads ahead of the previous row's 16 stores (vmcnt(16)); attention epilogue waits vmcnt(1) so a group no longer waits for its own store
# speedup vs baseline: 1.0001x; 1.0001x over previous
.LBB0_517:
	v_lshlrev_b64 v[4:5], 12, v[176:177]
	v_lshl_add_u64 v[2:3], v[172:173], 0, v[4:5]
	global_load_dwordx2 v[6:7], v[2:3], off
	global_load_dwordx2 v[8:9], v[2:3], off offset:16
	v_rcp_f32_e32 v0, v163
	v_lshl_add_u64 v[4:5], v[170:171], 0, v[4:5]
	s_mov_b64 s[78:79], 0
	s_and_b64 vcc, exec, s[4:5]
	v_mul_f32_e32 v10, v0, v64
	v_mul_f32_e32 v11, v0, v65
	v_mul_f32_e32 v12, v0, v66
	v_mul_f32_e32 v13, v0, v67
	v_mul_f32_e32 v14, v0, v68
	v_mul_f32_e32 v15, v0, v69
	v_mul_f32_e32 v64, v0, v70
	v_mul_f32_e32 v65, v0, v71
	s_waitcnt vmcnt(0)
	v_lshlrev_b32_e32 v66, 16, v6
	v_and_b32_e32 v6, 0xffff0000, v6
	v_lshlrev_b32_e32 v67, 16, v7
	v_and_b32_e32 v7, 0xffff0000, v7
	v_lshlrev_b32_e32 v68, 16, v8
	v_and_b32_e32 v8, 0xffff0000, v8
	v_lshlrev_b32_e32 v69, 16, v9
	v_and_b32_e32 v9, 0xffff0000, v9
	v_mul_f32_e32 v10, v10, v66
	v_mul_f32_e32 v6, v11, v6
	v_mul_f32_e32 v11, v12, v67
	v_mul_f32_e32 v7, v13, v7
	v_mul_f32_e32 v12, v14, v68
	v_mul_f32_e32 v8, v15, v8
	v_mul_f32_e32 v13, v64, v69
	v_mul_f32_e32 v9, v65, v9
	v_cvt_pk_bf16_f32 v6, v10, v6
	v_cvt_pk_bf16_f32 v7, v11, v7
	v_cvt_pk_bf16_f32 v8, v12, v8
	v_cvt_pk_bf16_f32 v9, v13, v9
	global_load_dwordx2 v[10:11], v[2:3], off offset:32
	global_load_dwordx2 v[12:13], v[2:3], off offset:48
	v_permlane32_swap_b32_e32 v6, v8
	v_permlane32_swap_b32_e32 v7, v9
	v_mul_f32_e32 v14, v0, v72
	v_mul_f32_e32 v15, v0, v73
	v_mul_f32_e32 v64, v0, v74
	v_mul_f32_e32 v65, v0, v75
	v_mul_f32_e32 v66, v0, v76
	v_mul_f32_e32 v67, v0, v77
	v_mul_f32_e32 v68, v0, v78
	v_mul_f32_e32 v69, v0, v79
	global_store_dwordx4 v[4:5], v[6:9], off
	s_waitcnt vmcnt(1)
	s_nop 0
	v_lshlrev_b32_e32 v6, 16, v10
	v_and_b32_e32 v7, 0xffff0000, v10
	v_lshlrev_b32_e32 v8, 16, v11
	v_and_b32_e32 v9, 0xffff0000, v11
	v_lshlrev_b32_e32 v10, 16, v12
	v_and_b32_e32 v11, 0xffff0000, v12
	v_lshlrev_b32_e32 v12, 16, v13
	v_and_b32_e32 v13, 0xffff0000, v13
	v_mul_f32_e32 v6, v14, v6
	v_mul_f32_e32 v7, v15, v7
	v_mul_f32_e32 v8, v64, v8
	v_mul_f32_e32 v9, v65, v9
	v_mul_f32_e32 v10, v66, v10
	v_mul_f32_e32 v11, v67, v11
	v_mul_f32_e32 v12, v68, v12
	v_mul_f32_e32 v13, v69, v13
	v_cvt_pk_bf16_f32 v6, v6, v7
	v_cvt_pk_bf16_f32 v7, v8, v9
	v_cvt_pk_bf16_f32 v8, v10, v11
	v_cvt_pk_bf16_f32 v9, v12, v13
	global_load_dwordx2 v[10:11], v[2:3], off offset:64
	global_load_dwordx2 v[12:13], v[2:3], off offset:80
	v_permlane32_swap_b32_e32 v6, v8
	v_permlane32_swap_b32_e32 v7, v9
	v_mul_f32_e32 v14, v0, v48
	v_mul_f32_e32 v15, v0, v49
	v_mul_f32_e32 v48, v0, v50
	v_mul_f32_e32 v49, v0, v51
	v_mul_f32_e32 v50, v0, v52
	v_mul_f32_e32 v51, v0, v53
	v_mul_f32_e32 v52, v0, v54
	v_mul_f32_e32 v53, v0, v55
	global_store_dwordx4 v[4:5], v[6:9], off offset:32
	s_waitcnt vmcnt(1)
	s_nop 0
	v_lshlrev_b32_e32 v6, 16, v10
	v_and_b32_e32 v7, 0xffff0000, v10
	v_lshlrev_b32_e32 v8, 16, v11
	v_and_b32_e32 v9, 0xffff0000, v11
	v_lshlrev_b32_e32 v10, 16, v12
	v_and_b32_e32 v11, 0xffff0000, v12
	v_lshlrev_b32_e32 v12, 16, v13
	v_and_b32_e32 v13, 0xffff0000, v13
	v_mul_f32_e32 v6, v14, v6
	v_mul_f32_e32 v7, v15, v7
	v_mul_f32_e32 v8, v48, v8
	v_mul_f32_e32 v9, v49, v9
	v_mul_f32_e32 v10, v50, v10
	v_mul_f32_e32 v11, v51, v11
	v_mul_f32_e32 v12, v52, v12
	v_mul_f32_e32 v13, v53, v13
	v_cvt_pk_bf16_f32 v6, v6, v7
	v_cvt_pk_bf16_f32 v7, v8, v9
	v_cvt_pk_bf16_f32 v8, v10, v11
	v_cvt_pk_bf16_f32 v9, v12, v13
	global_load_dwordx2 v[10:11], v[2:3], off offset:96
	global_load_dwordx2 v[12:13], v[2:3], off offset:112
	v_permlane32_swap_b32_e32 v6, v8
	v_permlane32_swap_b32_e32 v7, v9
	v_mul_f32_e32 v14, v0, v56
	v_mul_f32_e32 v15, v0, v57
	v_mul_f32_e32 v48, v0, v58
	v_mul_f32_e32 v49, v0, v59
	v_mul_f32_e32 v50, v0, v60
	v_mul_f32_e32 v51, v0, v61
	v_mul_f32_e32 v52, v0, v62
	v_mul_f32_e32 v53, v0, v63
	global_store_dwordx4 v[4:5], v[6:9], off offset:64
	s_waitcnt vmcnt(1)
	s_nop 0
	v_lshlrev_b32_e32 v6, 16, v10
	v_and_b32_e32 v7, 0xffff0000, v10
	v_lshlrev_b32_e32 v8, 16, v11
	v_and_b32_e32 v9, 0xffff0000, v11
	v_lshlrev_b32_e32 v10, 16, v12
	v_and_b32_e32 v11, 0xffff0000, v12
	v_lshlrev_b32_e32 v12, 16, v13
	v_and_b32_e32 v13, 0xffff0000, v13
	v_mul_f32_e32 v6, v14, v6
	v_mul_f32_e32 v7, v15, v7
	v_mul_f32_e32 v8, v48, v8
	v_mul_f32_e32 v9, v49, v9
	v_mul_f32_e32 v10, v50, v10
	v_mul_f32_e32 v11, v51, v11
	v_mul_f32_e32 v12, v52, v12
	v_mul_f32_e32 v13, v53, v13
	v_cvt_pk_bf16_f32 v6, v6, v7
	v_cvt_pk_bf16_f32 v7, v8, v9
	v_cvt_pk_bf16_f32 v8, v10, v11
	v_cvt_pk_bf16_f32 v9, v12, v13
	global_load_dwordx2 v[10:11], v[2:3], off offset:128
	global_load_dwordx2 v[12:13], v[2:3], off offset:144
	v_permlane32_swap_b32_e32 v6, v8
	v_permlane32_swap_b32_e32 v7, v9
	v_mul_f32_e32 v14, v0, v32
	v_mul_f32_e32 v15, v0, v33
	v_mul_f32_e32 v32, v0, v34
	v_mul_f32_e32 v33, v0, v35
	v_mul_f32_e32 v34, v0, v36
	v_mul_f32_e32 v35, v0, v37
	v_mul_f32_e32 v36, v0, v38
	v_mul_f32_e32 v37, v0, v39
	global_store_dwordx4 v[4:5], v[6:9], off offset:96
	s_waitcnt vmcnt(1)
	s_nop 0
	v_lshlrev_b32_e32 v6, 16, v10
	v_and_b32_e32 v7, 0xffff0000, v10
	v_lshlrev_b32_e32 v8, 16, v11
	v_and_b32_e32 v9, 0xffff0000, v11
	v_lshlrev_b32_e32 v10, 16, v12
	v_and_b32_e32 v11, 0xffff0000, v12
	v_lshlrev_b32_e32 v12, 16, v13
	v_and_b32_e32 v13, 0xffff0000, v13
	v_mul_f32_e32 v6, v14, v6
	v_mul_f32_e32 v7, v15, v7
	v_mul_f32_e32 v8, v32, v8
	v_mul_f32_e32 v9, v33, v9
	v_mul_f32_e32 v10, v34, v10
	v_mul_f32_e32 v11, v35, v11
	v_mul_f32_e32 v12, v36, v12
	v_mul_f32_e32 v13, v37, v13
	v_cvt_pk_bf16_f32 v6, v6, v7
	v_cvt_pk_bf16_f32 v7, v8, v9
	v_cvt_pk_bf16_f32 v8, v10, v11
	v_cvt_pk_bf16_f32 v9, v12, v13
	global_load_dwordx2 v[10:11], v[2:3], off offset:160
	global_load_dwordx2 v[12:13], v[2:3], off offset:176
	v_permlane32_swap_b32_e32 v6, v8
	v_permlane32_swap_b32_e32 v7, v9
	v_mul_f32_e32 v14, v0, v40
	v_mul_f32_e32 v15, v0, v41
	v_mul_f32_e32 v32, v0, v42
	v_mul_f32_e32 v33, v0, v43
	v_mul_f32_e32 v34, v0, v44
	v_mul_f32_e32 v35, v0, v45
	v_mul_f32_e32 v36, v0, v46
	v_mul_f32_e32 v37, v0, v47
	global_store_dwordx4 v[4:5], v[6:9], off offset:128
	s_waitcnt vmcnt(1)
	s_nop 0
	v_lshlrev_b32_e32 v6, 16, v10
	v_and_b32_e32 v7, 0xffff0000, v10
	v_lshlrev_b32_e32 v8, 16, v11
	v_and_b32_e32 v9, 0xffff0000, v11
	v_lshlrev_b32_e32 v10, 16, v12
	v_and_b32_e32 v11, 0xffff0000, v12
	v_lshlrev_b32_e32 v12, 16, v13
	v_and_b32_e32 v13, 0xffff0000, v13
	v_mul_f32_e32 v6, v14, v6
	v_mul_f32_e32 v7, v15, v7
	v_mul_f32_e32 v8, v32, v8
	v_mul_f32_e32 v9, v33, v9
	v_mul_f32_e32 v10, v34, v10
	v_mul_f32_e32 v11, v35, v11
	v_mul_f32_e32 v12, v36, v12
	v_mul_f32_e32 v13, v37, v13
	v_cvt_pk_bf16_f32 v6, v6, v7
	v_cvt_pk_bf16_f32 v7, v8, v9
	v_cvt_pk_bf16_f32 v8, v10, v11
	v_cvt_pk_bf16_f32 v9, v12, v13
	global_load_dwordx2 v[10:11], v[2:3], off offset:192
	global_load_dwordx2 v[12:13], v[2:3], off offset:208
	v_permlane32_swap_b32_e32 v6, v8
	v_permlane32_swap_b32_e32 v7, v9
	v_mul_f32_e32 v14, v0, v16
	v_mul_f32_e32 v15, v0, v17
	v_mul_f32_e32 v16, v0, v18
	v_mul_f32_e32 v17, v0, v19
	v_mul_f32_e32 v18, v0, v20
	v_mul_f32_e32 v19, v0, v21
	global_store_dwordx4 v[4:5], v[6:9], off offset:160
	v_mul_f32_e32 v20, v0, v22
	v_mul_f32_e32 v21, v0, v23
	s_waitcnt vmcnt(1)
	v_lshlrev_b32_e32 v6, 16, v10
	v_and_b32_e32 v7, 0xffff0000, v10
	v_lshlrev_b32_e32 v8, 16, v11
	v_and_b32_e32 v9, 0xffff0000, v11
	v_lshlrev_b32_e32 v10, 16, v12
	v_and_b32_e32 v11, 0xffff0000, v12
	v_lshlrev_b32_e32 v12, 16, v13
	v_and_b32_e32 v13, 0xffff0000, v13
	v_mul_f32_e32 v6, v14, v6
	v_mul_f32_e32 v7, v15, v7
	v_mul_f32_e32 v8, v16, v8
	v_mul_f32_e32 v9, v17, v9
	v_mul_f32_e32 v10, v18, v10
	v_mul_f32_e32 v11, v19, v11
	v_mul_f32_e32 v12, v20, v12
	v_mul_f32_e32 v13, v21, v13
	v_cvt_pk_bf16_f32 v6, v6, v7
	v_cvt_pk_bf16_f32 v7, v8, v9
	v_cvt_pk_bf16_f32 v8, v10, v11
	v_cvt_pk_bf16_f32 v9, v12, v13
	global_load_dwordx2 v[10:11], v[2:3], off offset:224
	s_nop 0
	global_load_dwordx2 v[2:3], v[2:3], off offset:240
	v_permlane32_swap_b32_e32 v6, v8
	v_permlane32_swap_b32_e32 v7, v9
	v_mul_f32_e32 v12, v0, v24
	v_mul_f32_e32 v13, v0, v25
	v_mul_f32_e32 v14, v0, v26
	v_mul_f32_e32 v15, v0, v27
	global_store_dwordx4 v[4:5], v[6:9], off offset:192
	v_mul_f32_e32 v16, v0, v28
	v_mul_f32_e32 v17, v0, v29
	v_mul_f32_e32 v18, v0, v30
	v_mul_f32_e32 v0, v0, v31
	s_waitcnt vmcnt(1)
	v_lshlrev_b32_e32 v6, 16, v10
	v_and_b32_e32 v7, 0xffff0000, v10
	v_lshlrev_b32_e32 v8, 16, v11
	v_and_b32_e32 v9, 0xffff0000, v11
	v_lshlrev_b32_e32 v10, 16, v2
	v_and_b32_e32 v2, 0xffff0000, v2
	v_lshlrev_b32_e32 v11, 16, v3
	v_and_b32_e32 v3, 0xffff0000, v3
	v_mul_f32_e32 v6, v12, v6
	v_mul_f32_e32 v7, v13, v7
	v_mul_f32_e32 v8, v14, v8
	v_mul_f32_e32 v9, v15, v9
	v_mul_f32_e32 v10, v16, v10
	v_mul_f32_e32 v2, v17, v2
	v_mul_f32_e32 v11, v18, v11
	v_mul_f32_e32 v0, v0, v3
	v_cvt_pk_bf16_f32 v6, v6, v7
	v_cvt_pk_bf16_f32 v7, v8, v9
	v_cvt_pk_bf16_f32 v8, v10, v2
	v_cvt_pk_bf16_f32 v9, v11, v0
	s_nop 0
	v_permlane32_swap_b32_e32 v6, v8
	v_permlane32_swap_b32_e32 v7, v9
	global_store_dwordx4 v[4:5], v[6:9], off offset:224
	s_waitcnt vmcnt(0) lgkmcnt(0)
	s_barrier
	s_cbranch_vccnz .LBB0_559

.LBB0_560:
	v_lshlrev_b64 v[4:5], 1, v[150:151]
	v_lshl_add_u64 v[2:3], v[172:173], 0, v[4:5]
	global_load_dwordx2 v[6:7], v[2:3], off offset:2048
	global_load_dwordx2 v[8:9], v[2:3], off offset:2064
	v_rcp_f32_e32 v0, v154
	v_lshl_add_u64 v[4:5], v[170:171], 0, v[4:5]
	s_mov_b64 s[84:85], 0
	s_and_b64 vcc, exec, s[4:5]
	v_mul_f32_e32 v10, v0, v64
	v_mul_f32_e32 v11, v0, v65
	v_mul_f32_e32 v12, v0, v66
	v_mul_f32_e32 v13, v0, v67
	v_mul_f32_e32 v14, v0, v68
	v_mul_f32_e32 v15, v0, v69
	v_mul_f32_e32 v64, v0, v70
	v_mul_f32_e32 v65, v0, v71
	s_waitcnt vmcnt(0)
	v_lshlrev_b32_e32 v66, 16, v6
	v_and_b32_e32 v6, 0xffff0000, v6
	v_lshlrev_b32_e32 v67, 16, v7
	v_and_b32_e32 v7, 0xffff0000, v7
	v_lshlrev_b32_e32 v68, 16, v8
	v_and_b32_e32 v8, 0xffff0000, v8
	v_lshlrev_b32_e32 v69, 16, v9
	v_and_b32_e32 v9, 0xffff0000, v9
	v_mul_f32_e32 v10, v10, v66
	v_mul_f32_e32 v6, v11, v6
	v_mul_f32_e32 v11, v12, v67
	v_mul_f32_e32 v7, v13, v7
	v_mul_f32_e32 v12, v14, v68
	v_mul_f32_e32 v8, v15, v8
	v_mul_f32_e32 v13, v64, v69
	v_mul_f32_e32 v9, v65, v9
	v_cvt_pk_bf16_f32 v6, v10, v6
	v_cvt_pk_bf16_f32 v7, v11, v7
	v_cvt_pk_bf16_f32 v8, v12, v8
	v_cvt_pk_bf16_f32 v9, v13, v9
	global_load_dwordx2 v[10:11], v[2:3], off offset:2080
	global_load_dwordx2 v[12:13], v[2:3], off offset:2096
	v_permlane32_swap_b32_e32 v6, v8
	v_permlane32_swap_b32_e32 v7, v9
	v_mul_f32_e32 v14, v0, v72
	v_mul_f32_e32 v15, v0, v73
	v_mul_f32_e32 v64, v0, v74
	v_mul_f32_e32 v65, v0, v75
	v_mul_f32_e32 v66, v0, v76
	v_mul_f32_e32 v67, v0, v77
	v_mul_f32_e32 v68, v0, v78
	v_mul_f32_e32 v69, v0, v79
	global_store_dwordx4 v[4:5], v[6:9], off offset:2048
	s_waitcnt vmcnt(1)
	s_nop 0
	v_lshlrev_b32_e32 v6, 16, v10
	v_and_b32_e32 v7, 0xffff0000, v10
	v_lshlrev_b32_e32 v8, 16, v11
	v_and_b32_e32 v9, 0xffff0000, v11
	v_lshlrev_b32_e32 v10, 16, v12
	v_and_b32_e32 v11, 0xffff0000, v12
	v_lshlrev_b32_e32 v12, 16, v13
	v_and_b32_e32 v13, 0xffff0000, v13
	v_mul_f32_e32 v6, v14, v6
	v_mul_f32_e32 v7, v15, v7
	v_mul_f32_e32 v8, v64, v8
	v_mul_f32_e32 v9, v65, v9
	v_mul_f32_e32 v10, v66, v10
	v_mul_f32_e32 v11, v67, v11
	v_mul_f32_e32 v12, v68, v12
	v_mul_f32_e32 v13, v69, v13
	v_cvt_pk_bf16_f32 v6, v6, v7
	v_cvt_pk_bf16_f32 v7, v8, v9
	v_cvt_pk_bf16_f32 v8, v10, v11
	v_cvt_pk_bf16_f32 v9, v12, v13
	global_load_dwordx2 v[10:11], v[2:3], off offset:2112
	global_load_dwordx2 v[12:13], v[2:3], off offset:2128
	v_permlane32_swap_b32_e32 v6, v8
	v_permlane32_swap_b32_e32 v7, v9
	v_mul_f32_e32 v14, v0, v48
	v_mul_f32_e32 v15, v0, v49
	v_mul_f32_e32 v48, v0, v50
	v_mul_f32_e32 v49, v0, v51
	v_mul_f32_e32 v50, v0, v52
	v_mul_f32_e32 v51, v0, v53
	v_mul_f32_e32 v52, v0, v54
	v_mul_f32_e32 v53, v0, v55
	global_store_dwordx4 v[4:5], v[6:9], off offset:2080
	s_waitcnt vmcnt(1)
	s_nop 0
	v_lshlrev_b32_e32 v6, 16, v10
	v_and_b32_e32 v7, 0xffff0000, v10
	v_lshlrev_b32_e32 v8, 16, v11
	v_and_b32_e32 v9, 0xffff0000, v11
	v_lshlrev_b32_e32 v10, 16, v12
	v_and_b32_e32 v11, 0xffff0000, v12
	v_lshlrev_b32_e32 v12, 16, v13
	v_and_b32_e32 v13, 0xffff0000, v13
	v_mul_f32_e32 v6, v14, v6
	v_mul_f32_e32 v7, v15, v7
	v_mul_f32_e32 v8, v48, v8
	v_mul_f32_e32 v9, v49, v9
	v_mul_f32_e32 v10, v50, v10
	v_mul_f32_e32 v11, v51, v11
	v_mul_f32_e32 v12, v52, v12
	v_mul_f32_e32 v13, v53, v13
	v_cvt_pk_bf16_f32 v6, v6, v7
	v_cvt_pk_bf16_f32 v7, v8, v9
	v_cvt_pk_bf16_f32 v8, v10, v11
	v_cvt_pk_bf16_f32 v9, v12, v13
	global_load_dwordx2 v[10:11], v[2:3], off offset:2144
	global_load_dwordx2 v[12:13], v[2:3], off offset:2160
	v_permlane32_swap_b32_e32 v6, v8
	v_permlane32_swap_b32_e32 v7, v9
	v_mul_f32_e32 v14, v0, v56
	v_mul_f32_e32 v15, v0, v57
	v_mul_f32_e32 v48, v0, v58
	v_mul_f32_e32 v49, v0, v59
	v_mul_f32_e32 v50, v0, v60
	v_mul_f32_e32 v51, v0, v61
	v_mul_f32_e32 v52, v0, v62
	v_mul_f32_e32 v53, v0, v63
	global_store_dwordx4 v[4:5], v[6:9], off offset:2112
	s_waitcnt vmcnt(1)
	s_nop 0
	v_lshlrev_b32_e32 v6, 16, v10
	v_and_b32_e32 v7, 0xffff0000, v10
	v_lshlrev_b32_e32 v8, 16, v11
	v_and_b32_e32 v9, 0xffff0000, v11
	v_lshlrev_b32_e32 v10, 16, v12
	v_and_b32_e32 v11, 0xffff0000, v12
	v_lshlrev_b32_e32 v12, 16, v13
	v_and_b32_e32 v13, 0xffff0000, v13
	v_mul_f32_e32 v6, v14, v6
	v_mul_f32_e32 v7, v15, v7
	v_mul_f32_e32 v8, v48, v8
	v_mul_f32_e32 v9, v49, v9
	v_mul_f32_e32 v10, v50, v10
	v_mul_f32_e32 v11, v51, v11
	v_mul_f32_e32 v12, v52, v12
	v_mul_f32_e32 v13, v53, v13
	v_cvt_pk_bf16_f32 v6, v6, v7
	v_cvt_pk_bf16_f32 v7, v8, v9
	v_cvt_pk_bf16_f32 v8, v10, v11
	v_cvt_pk_bf16_f32 v9, v12, v13
	global_load_dwordx2 v[10:11], v[2:3], off offset:2176
	global_load_dwordx2 v[12:13], v[2:3], off offset:2192
	v_permlane32_swap_b32_e32 v6, v8
	v_permlane32_swap_b32_e32 v7, v9
	v_mul_f32_e32 v14, v0, v32
	v_mul_f32_e32 v15, v0, v33
	v_mul_f32_e32 v32, v0, v34
	v_mul_f32_e32 v33, v0, v35
	v_mul_f32_e32 v34, v0, v36
	v_mul_f32_e32 v35, v0, v37
	v_mul_f32_e32 v36, v0, v38
	v_mul_f32_e32 v37, v0, v39
	global_store_dwordx4 v[4:5], v[6:9], off offset:2144
	s_waitcnt vmcnt(1)
	s_nop 0
	v_lshlrev_b32_e32 v6, 16, v10
	v_and_b32_e32 v7, 0xffff0000, v10
	v_lshlrev_b32_e32 v8, 16, v11
	v_and_b32_e32 v9, 0xffff0000, v11
	v_lshlrev_b32_e32 v10, 16, v12
	v_and_b32_e32 v11, 0xffff0000, v12
	v_lshlrev_b32_e32 v12, 16, v13
	v_and_b32_e32 v13, 0xffff0000, v13
	v_mul_f32_e32 v6, v14, v6
	v_mul_f32_e32 v7, v15, v7
	v_mul_f32_e32 v8, v32, v8
	v_mul_f32_e32 v9, v33, v9
	v_mul_f32_e32 v10, v34, v10
	v_mul_f32_e32 v11, v35, v11
	v_mul_f32_e32 v12, v36, v12
	v_mul_f32_e32 v13, v37, v13
	v_cvt_pk_bf16_f32 v6, v6, v7
	v_cvt_pk_bf16_f32 v7, v8, v9
	v_cvt_pk_bf16_f32 v8, v10, v11
	v_cvt_pk_bf16_f32 v9, v12, v13
	global_load_dwordx2 v[10:11], v[2:3], off offset:2208
	global_load_dwordx2 v[12:13], v[2:3], off offset:2224
	v_permlane32_swap_b32_e32 v6, v8
	v_permlane32_swap_b32_e32 v7, v9
	v_mul_f32_e32 v14, v0, v40
	v_mul_f32_e32 v15, v0, v41
	v_mul_f32_e32 v32, v0, v42
	v_mul_f32_e32 v33, v0, v43
	v_mul_f32_e32 v34, v0, v44
	v_mul_f32_e32 v35, v0, v45
	v_mul_f32_e32 v36, v0, v46
	v_mul_f32_e32 v37, v0, v47
	global_store_dwordx4 v[4:5], v[6:9], off offset:2176
	s_waitcnt vmcnt(1)
	s_nop 0
	v_lshlrev_b32_e32 v6, 16, v10
	v_and_b32_e32 v7, 0xffff0000, v10
	v_lshlrev_b32_e32 v8, 16, v11
	v_and_b32_e32 v9, 0xffff0000, v11
	v_lshlrev_b32_e32 v10, 16, v12
	v_and_b32_e32 v11, 0xffff0000, v12
	v_lshlrev_b32_e32 v12, 16, v13
	v_and_b32_e32 v13, 0xffff0000, v13
	v_mul_f32_e32 v6, v14, v6
	v_mul_f32_e32 v7, v15, v7
	v_mul_f32_e32 v8, v32, v8
	v_mul_f32_e32 v9, v33, v9
	v_mul_f32_e32 v10, v34, v10
	v_mul_f32_e32 v11, v35, v11
	v_mul_f32_e32 v12, v36, v12
	v_mul_f32_e32 v13, v37, v13
	v_cvt_pk_bf16_f32 v6, v6, v7
	v_cvt_pk_bf16_f32 v7, v8, v9
	v_cvt_pk_bf16_f32 v8, v10, v11
	v_cvt_pk_bf16_f32 v9, v12, v13
	global_load_dwordx2 v[10:11], v[2:3], off offset:2240
	global_load_dwordx2 v[12:13], v[2:3], off offset:2256
	v_permlane32_swap_b32_e32 v6, v8
	v_permlane32_swap_b32_e32 v7, v9
	v_mul_f32_e32 v14, v0, v16
	v_mul_f32_e32 v15, v0, v17
	v_mul_f32_e32 v16, v0, v18
	v_mul_f32_e32 v17, v0, v19
	v_mul_f32_e32 v18, v0, v20
	v_mul_f32_e32 v19, v0, v21
	global_store_dwordx4 v[4:5], v[6:9], off offset:2208
	v_mul_f32_e32 v20, v0, v22
	v_mul_f32_e32 v21, v0, v23
	s_waitcnt vmcnt(1)
	v_lshlrev_b32_e32 v6, 16, v10
	v_and_b32_e32 v7, 0xffff0000, v10
	v_lshlrev_b32_e32 v8, 16, v11
	v_and_b32_e32 v9, 0xffff0000, v11
	v_lshlrev_b32_e32 v10, 16, v12
	v_and_b32_e32 v11, 0xffff0000, v12
	v_lshlrev_b32_e32 v12, 16, v13
	v_and_b32_e32 v13, 0xffff0000, v13
	v_mul_f32_e32 v6, v14, v6
	v_mul_f32_e32 v7, v15, v7
	v_mul_f32_e32 v8, v16, v8
	v_mul_f32_e32 v9, v17, v9
	v_mul_f32_e32 v10, v18, v10
	v_mul_f32_e32 v11, v19, v11
	v_mul_f32_e32 v12, v20, v12
	v_mul_f32_e32 v13, v21, v13
	v_cvt_pk_bf16_f32 v6, v6, v7
	v_cvt_pk_bf16_f32 v7, v8, v9
	v_cvt_pk_bf16_f32 v8, v10, v11
	v_cvt_pk_bf16_f32 v9, v12, v13
	global_load_dwordx2 v[10:11], v[2:3], off offset:2272
	s_nop 0
	global_load_dwordx2 v[2:3], v[2:3], off offset:2288
	v_permlane32_swap_b32_e32 v6, v8
	v_permlane32_swap_b32_e32 v7, v9
	v_mul_f32_e32 v12, v0, v24
	v_mul_f32_e32 v13, v0, v25
	v_mul_f32_e32 v14, v0, v26
	v_mul_f32_e32 v15, v0, v27
	global_store_dwordx4 v[4:5], v[6:9], off offset:2240
	v_mul_f32_e32 v16, v0, v28
	v_mul_f32_e32 v17, v0, v29
	v_mul_f32_e32 v18, v0, v30
	v_mul_f32_e32 v0, v0, v31
	s_waitcnt vmcnt(1)
	v_lshlrev_b32_e32 v6, 16, v10
	v_and_b32_e32 v7, 0xffff0000, v10
	v_lshlrev_b32_e32 v8, 16, v11
	v_and_b32_e32 v9, 0xffff0000, v11
	v_lshlrev_b32_e32 v10, 16, v2
	v_and_b32_e32 v2, 0xffff0000, v2
	v_lshlrev_b32_e32 v11, 16, v3
	v_and_b32_e32 v3, 0xffff0000, v3
	v_mul_f32_e32 v6, v12, v6
	v_mul_f32_e32 v7, v13, v7
	v_mul_f32_e32 v8, v14, v8
	v_mul_f32_e32 v9, v15, v9
	v_mul_f32_e32 v10, v16, v10
	v_mul_f32_e32 v2, v17, v2
	v_mul_f32_e32 v11, v18, v11
	v_mul_f32_e32 v0, v0, v3
	v_cvt_pk_bf16_f32 v6, v6, v7
	v_cvt_pk_bf16_f32 v7, v8, v9
	v_cvt_pk_bf16_f32 v8, v10, v2
	v_cvt_pk_bf16_f32 v9, v11, v0
	s_nop 0
	v_permlane32_swap_b32_e32 v6, v8
	v_permlane32_swap_b32_e32 v7, v9
	global_store_dwordx4 v[4:5], v[6:9], off offset:2272
	s_waitcnt vmcnt(0) lgkmcnt(0)
	s_barrier
	s_cbranch_vccnz .LBB0_515
